# v47: v41 + cross-item prefetch in P2: each HGRN wave issues the first operand loads of its second prompt item during its first item
# baseline (speedup 1.0000x reference)
.LBB0_591:
	v_add_u32_e32 v52, s12, v61
	s_mov_b64 s[0:1], -1
	s_and_b64 vcc, exec, s[40:41]
	v_lshlrev_b32_e32 v50, 1, v60
	s_cbranch_vccz .LBB0_600
	s_lshl_b32 s0, s16, 7
	v_mov_b64_e32 v[2:3], s[58:59]
	s_add_i32 s40, s0, 0xfffffe00
	v_mad_i64_i32 v[2:3], s[0:1], v52, s89, v[2:3]
	s_mov_b32 s41, s61
	v_lshl_add_u64 v[2:3], s[40:41], 1, v[2:3]
	v_mov_b32_e32 v51, v57
	v_lshl_add_u64 v[38:39], v[2:3], 0, v[50:51]
	v_add_co_u32_e32 v2, vcc, 0x1000, v38
	s_mov_b64 s[0:1], 0x1000
	s_nop 0
	v_addc_co_u32_e32 v3, vcc, 0, v39, vcc
	s_cmp_lt_u32 s56, 0x800
	s_cbranch_scc0 .Lpfh_use
	global_load_dwordx4 v[22:25], v[2:3], off
	global_load_dwordx4 v[18:21], v[38:39], off offset:3072
	s_mov_b32 s100, 0x3800000
	s_mov_b32 s101, 0
	v_lshl_add_u64 v[230:231], v[2:3], 0, s[100:101]
	v_lshl_add_u64 v[246:247], v[38:39], 0, s[100:101]
	global_load_dwordx4 v[222:225], v[230:231], off
	global_load_dwordx4 v[226:229], v[246:247], off offset:3072
	s_branch .Lpfh_done
.Lpfh_use:
	s_waitcnt vmcnt(0)
	v_mov_b32_e32 v22, v222
	v_mov_b32_e32 v23, v223
	v_mov_b32_e32 v24, v224
	v_mov_b32_e32 v25, v225
	v_mov_b32_e32 v18, v226
	v_mov_b32_e32 v19, v227
	v_mov_b32_e32 v20, v228
	v_mov_b32_e32 v21, v229
.Lpfh_done:
	v_mov_b32_e32 v2, 0
	s_mov_b32 s17, 0
	s_mov_b32 s42, 16
	v_lshl_add_u32 v51, s16, 9, v182
	v_mov_b32_e32 v53, v63
	v_mov_b32_e32 v56, v184
	v_mov_b32_e32 v3, v2
	v_mov_b32_e32 v4, v2
	v_mov_b32_e32 v5, v2
	v_mov_b32_e32 v6, v2
	v_mov_b32_e32 v7, v2
	v_mov_b32_e32 v8, v2
	v_mov_b32_e32 v9, v2
	v_mov_b32_e32 v10, v2
	v_mov_b32_e32 v11, v2
	v_mov_b32_e32 v12, v2
	v_mov_b32_e32 v13, v2
	v_mov_b32_e32 v14, v2
	v_mov_b32_e32 v15, v2
	v_mov_b32_e32 v16, v2
	v_lshl_add_u64 v[40:41], v[38:39], 0, s[0:1]
	v_mov_b32_e32 v17, v2
	s_waitcnt vmcnt(1)
	v_lshlrev_b32_e32 v30, 16, v22
	v_and_b32_e32 v31, 0xffff0000, v22
	v_lshlrev_b32_e32 v32, 16, v23
	v_and_b32_e32 v33, 0xffff0000, v23
	v_lshlrev_b32_e32 v75, 16, v24
	v_and_b32_e32 v77, 0xffff0000, v24
	v_lshlrev_b32_e32 v71, 16, v25
	v_and_b32_e32 v73, 0xffff0000, v25
	s_branch .LBB0_594
